# layer-1 input projection tile order: the two V column tiles land in different rounds (workgroups 64-127 in round 0, 192-255 in round 1) so their transposed-store bursts do not coincide
# baseline (speedup 1.0000x reference)
.LBB0_44:
	s_lshl_b32 s8, s14, 3
	v_cvt_f32_u32_e32 v0, s8
	s_sub_i32 s9, 0, s8
	s_ashr_i32 s7, s7, 3
	s_add_i32 s7, s10, s7
	v_rcp_iflag_f32_e32 v0, v0
	s_abs_i32 s11, s7
	s_ashr_i32 s10, s7, 31
	v_mul_f32_e32 v0, 0x4f7ffffe, v0
	v_cvt_u32_f32_e32 v0, v0
	s_nop 0
	v_readfirstlane_b32 s12, v0
	s_mul_i32 s9, s9, s12
	s_mul_hi_u32 s9, s12, s9
	s_add_i32 s12, s12, s9
	s_mul_hi_u32 s9, s11, s12
	s_mul_i32 s12, s9, s8
	s_sub_i32 s11, s11, s12
	s_add_i32 s13, s9, 1
	s_sub_i32 s12, s11, s8
	s_cmp_ge_u32 s11, s8
	s_cselect_b32 s9, s13, s9
	s_cselect_b32 s11, s12, s11
	s_add_i32 s12, s9, 1
	s_cmp_ge_u32 s11, s8
	s_cselect_b32 s9, s12, s9
	s_xor_b32 s9, s9, s10
	s_sub_i32 s9, s9, s10
	s_lshl_b32 s10, s9, 3
	s_mul_i32 s9, s9, s8
	v_readlane_b32 s8, v253, 61
	s_sub_i32 s8, s8, s10
	s_min_i32 s11, s8, 8
	s_sext_i32_i16 s8, s11
	v_cvt_f32_i32_e32 v0, s8
	s_sub_i32 s7, s7, s9
	s_sext_i32_i16 s9, s7
	v_cvt_f32_i32_e32 v2, s9
	v_rcp_iflag_f32_e32 v3, v0
	s_xor_b32 s8, s9, s8
	s_ashr_i32 s8, s8, 30
	s_or_b32 s12, s8, 1
	v_mul_f32_e32 v3, v2, v3
	v_trunc_f32_e32 v3, v3
	v_fma_f32 v2, -v3, v0, v2
	v_cvt_i32_f32_e32 v3, v3
	v_cmp_ge_f32_e64 s[8:9], |v2|, |v0|
	s_and_b64 s[8:9], s[8:9], exec
	s_cselect_b32 s8, s12, 0
	v_readfirstlane_b32 s9, v3
	s_add_i32 s8, s9, s8
	s_mul_i32 s11, s8, s11
	s_sub_i32 s7, s7, s11
	s_sext_i32_i16 s9, s8
	s_sext_i32_i16 s7, s7
	s_add_i32 s34, s10, s7
	s_add_i32 s7, s9, 1
	s_and_b32 s8, s8, 0xffff
	s_cmp_lg_u32 s8, 8
	s_cselect_b32 s7, s7, 0
	v_readlane_b32 s8, v253, 55
	s_cmp_eq_u32 s8, 1
	s_cbranch_scc0 .Lpn0_keep
	s_cmp_eq_u32 s7, 2
	s_cselect_b32 s7, 5, s7
.Lpn0_keep:
	s_cmp_eq_u32 s14, 9
	s_cselect_b32 s16, s7, s9
	s_andn2_b64 vcc, exec, s[4:5]
	s_cbranch_vccz .LBB0_47

.LBB0_60:
	s_ashr_i32 s0, s8, 3
	s_add_i32 s0, s14, s0
	s_abs_i32 s8, s0
	v_readlane_b32 s9, v254, 45
	s_mul_hi_u32 s9, s8, s9
	s_mul_i32 s14, s9, s69
	s_sub_i32 s8, s8, s14
	s_ashr_i32 s1, s0, 31
	s_add_i32 s14, s9, 1
	s_sub_i32 s15, s8, s69
	s_cmp_ge_u32 s8, s69
	s_cselect_b32 s9, s14, s9
	s_cselect_b32 s8, s15, s8
	s_add_i32 s14, s9, 1
	s_cmp_ge_u32 s8, s69
	s_cselect_b32 s8, s14, s9
	s_xor_b32 s8, s8, s1
	s_sub_i32 s1, s8, s1
	s_lshl_b32 s8, s1, 3
	v_readlane_b32 s9, v253, 61
	s_sub_i32 s9, s9, s8
	s_min_i32 s9, s9, 8
	s_abs_i32 s14, s9
	v_cvt_f32_u32_e32 v0, s14
	s_sub_i32 s17, 0, s14
	s_mul_i32 s1, s1, s69
	s_sub_i32 s0, s0, s1
	v_rcp_iflag_f32_e32 v0, v0
	s_abs_i32 s1, s0
	s_xor_b32 s15, s0, s9
	s_ashr_i32 s15, s15, 31
	v_mul_f32_e32 v0, 0x4f7ffffe, v0
	v_cvt_u32_f32_e32 v0, v0
	s_nop 0
	v_readfirstlane_b32 s18, v0
	s_mul_i32 s17, s17, s18
	s_mul_hi_u32 s17, s18, s17
	s_add_i32 s18, s18, s17
	s_mul_hi_u32 s17, s1, s18
	s_mul_i32 s18, s17, s14
	s_sub_i32 s1, s1, s18
	s_add_i32 s18, s17, 1
	s_sub_i32 s22, s1, s14
	s_cmp_ge_u32 s1, s14
	s_cselect_b32 s17, s18, s17
	s_cselect_b32 s1, s22, s1
	s_add_i32 s18, s17, 1
	s_cmp_ge_u32 s1, s14
	s_cselect_b32 s1, s18, s17
	s_xor_b32 s1, s1, s15
	s_sub_i32 s14, s1, s15
	s_mul_i32 s1, s14, s9
	s_sub_i32 s0, s0, s1
	s_add_i32 s97, s0, s8
	s_add_i32 s0, s14, 1
	s_cmp_lg_u32 s14, 8
	s_cselect_b32 s8, s0, 0
	v_readlane_b32 s0, v253, 55
	s_cmp_eq_u32 s0, 1
	s_cbranch_scc0 .Lpn_keep
	s_mov_b32 s0, s8
	s_cmp_eq_u32 s0, 5
	s_cselect_b32 s8, 7, s8
	s_cmp_eq_u32 s0, 6
	s_cselect_b32 s8, 2, s8
	s_cmp_eq_u32 s0, 7
	s_cselect_b32 s8, 8, s8
	s_cmp_eq_u32 s0, 8
	s_cselect_b32 s8, 6, s8
